# attention softmax: exponent argument with one v_fmamk per element (x*log2e - m*log2e) instead of sub+mul; cross-half max via v_permlane32_swap instead of an LDS bpermute
# speedup vs baseline: 1.0864x; 1.0055x over previous
.LBB0_632:
	v_mov_b32_e32 v212, v201
	s_nop 1
	v_permlane32_swap_b32_e32 v212, v201
	v_max3_f32 v201, v202, v201, v212
	v_mul_f32_e32 v213, 0xbfb8aa3b, v201
	v_fmamk_f32 v114, v114, 0x3fb8aa3b, v213
	v_fmamk_f32 v115, v115, 0x3fb8aa3b, v213
	v_exp_f32_e32 v114, v114
	v_fmamk_f32 v116, v116, 0x3fb8aa3b, v213
	v_fmamk_f32 v117, v117, 0x3fb8aa3b, v213
	v_exp_f32_e32 v115, v115
	v_exp_f32_e32 v116, v116
	v_exp_f32_e32 v117, v117
	v_add_f32_e32 v212, 0, v114
	v_add_f32_e32 v212, v115, v212
	v_add_f32_e32 v212, v116, v212
	v_cvt_pk_bf16_f32 v114, v114, v115
	v_cvt_pk_bf16_f32 v115, v116, v117
	v_fmamk_f32 v116, v118, 0x3fb8aa3b, v213
	v_add_f32_e32 v212, v117, v212
	v_fmamk_f32 v117, v119, 0x3fb8aa3b, v213
	v_fmamk_f32 v118, v120, 0x3fb8aa3b, v213
	v_fmamk_f32 v119, v121, 0x3fb8aa3b, v213
	v_exp_f32_e32 v116, v116
	v_exp_f32_e32 v117, v117
	v_exp_f32_e32 v118, v118
	v_exp_f32_e32 v119, v119
	v_add_f32_e32 v120, v116, v212
	v_add_f32_e32 v120, v117, v120
	v_cvt_pk_bf16_f32 v116, v116, v117
	v_cvt_pk_bf16_f32 v117, v118, v119
	ds_write2_b64 v195, v[114:115], v[116:117] offset1:2
	v_fmamk_f32 v114, v122, 0x3fb8aa3b, v213
	v_fmamk_f32 v115, v123, 0x3fb8aa3b, v213
	v_exp_f32_e32 v114, v114
	v_fmamk_f32 v116, v124, 0x3fb8aa3b, v213
	v_fmamk_f32 v117, v125, 0x3fb8aa3b, v213
	v_exp_f32_e32 v115, v115
	v_add_f32_e32 v120, v118, v120
	v_exp_f32_e32 v116, v116
	v_exp_f32_e32 v117, v117
	v_add_f32_e32 v120, v119, v120
	v_add_f32_e32 v118, v114, v120
	v_add_f32_e32 v118, v115, v118
	v_add_f32_e32 v118, v116, v118
	v_cvt_pk_bf16_f32 v114, v114, v115
	v_cvt_pk_bf16_f32 v115, v116, v117
	v_fmamk_f32 v116, v126, 0x3fb8aa3b, v213
	v_add_f32_e32 v118, v117, v118
	v_fmamk_f32 v117, v127, 0x3fb8aa3b, v213
	v_exp_f32_e32 v116, v116
	v_fmamk_f32 v119, v128, 0x3fb8aa3b, v213
	v_exp_f32_e32 v117, v117
	v_fmamk_f32 v120, v129, 0x3fb8aa3b, v213
	v_exp_f32_e32 v119, v119
	v_fmamk_f32 v98, v98, 0x3fb8aa3b, v213
	v_exp_f32_e32 v120, v120
	v_fmamk_f32 v99, v99, 0x3fb8aa3b, v213
	v_add_f32_e32 v118, v116, v118
	v_exp_f32_e32 v98, v98
	v_fmamk_f32 v100, v100, 0x3fb8aa3b, v213
	v_fmamk_f32 v101, v101, 0x3fb8aa3b, v213
	v_add_f32_e32 v118, v117, v118
	v_exp_f32_e32 v99, v99
	v_add_f32_e32 v118, v119, v118
	v_exp_f32_e32 v100, v100
	v_exp_f32_e32 v101, v101
	v_add_f32_e32 v118, v120, v118
	v_cvt_pk_bf16_f32 v116, v116, v117
	v_cvt_pk_bf16_f32 v117, v119, v120
	ds_write2_b64 v195, v[114:115], v[116:117] offset0:4 offset1:6
	v_add_f32_e32 v114, v98, v118
	v_add_f32_e32 v114, v99, v114
	v_add_f32_e32 v114, v100, v114
	v_cvt_pk_bf16_f32 v98, v98, v99
	v_cvt_pk_bf16_f32 v99, v100, v101
	v_fmamk_f32 v100, v102, 0x3fb8aa3b, v213
	v_add_f32_e32 v114, v101, v114
	v_fmamk_f32 v101, v103, 0x3fb8aa3b, v213
	v_fmamk_f32 v102, v104, 0x3fb8aa3b, v213
	v_fmamk_f32 v103, v105, 0x3fb8aa3b, v213
	v_exp_f32_e32 v100, v100
	v_exp_f32_e32 v101, v101
	v_exp_f32_e32 v102, v102
	v_exp_f32_e32 v103, v103
	v_add_f32_e32 v104, v100, v114
	v_add_f32_e32 v104, v101, v104
	v_cvt_pk_bf16_f32 v100, v100, v101
	v_cvt_pk_bf16_f32 v101, v102, v103
	ds_write2_b64 v195, v[98:99], v[100:101] offset0:8 offset1:10
	v_fmamk_f32 v98, v106, 0x3fb8aa3b, v213
	v_fmamk_f32 v99, v107, 0x3fb8aa3b, v213
	v_exp_f32_e32 v98, v98
	v_fmamk_f32 v100, v108, 0x3fb8aa3b, v213
	v_exp_f32_e32 v99, v99
	v_fmamk_f32 v101, v109, 0x3fb8aa3b, v213
	v_add_f32_e32 v104, v102, v104
	v_exp_f32_e32 v100, v100
	v_add_f32_e32 v104, v103, v104
	v_exp_f32_e32 v101, v101
	v_add_f32_e32 v102, v98, v104
	v_add_f32_e32 v102, v99, v102
	v_add_f32_e32 v102, v100, v102
	v_add_f32_e32 v104, v101, v102
	v_cvt_pk_bf16_f32 v102, v98, v99
	v_fmamk_f32 v99, v111, 0x3fb8aa3b, v213
	v_fmamk_f32 v98, v110, 0x3fb8aa3b, v213
	v_cvt_pk_bf16_f32 v103, v100, v101
	v_exp_f32_e32 v100, v99
	v_fmamk_f32 v99, v112, 0x3fb8aa3b, v213
	v_exp_f32_e32 v98, v98
	v_exp_f32_e32 v101, v99
	v_fmamk_f32 v99, v113, 0x3fb8aa3b, v213
	v_exp_f32_e32 v105, v99
	v_add_f32_e32 v99, v98, v104
	v_add_f32_e32 v99, v100, v99
	v_sub_f32_e32 v202, v202, v201
	v_add_f32_e32 v99, v101, v99
	v_mul_f32_e32 v202, 0x3fb8aa3b, v202
	v_add_f32_e32 v99, v105, v99
	v_cvt_pk_bf16_f32 v104, v98, v100
	v_exp_f32_e32 v98, v202
	ds_bpermute_b32 v100, v171, v99
	v_cvt_pk_bf16_f32 v105, v101, v105
	ds_write2_b64 v195, v[102:103], v[104:105] offset0:12 offset1:14
	v_cmp_neq_f32_e32 vcc, 1.0, v98
	s_cbranch_vccz .LBB0_634
	v_pk_mul_f32 v[64:65], v[64:65], v[98:99] op_sel_hi:[1,0]
	v_pk_mul_f32 v[62:63], v[62:63], v[98:99] op_sel_hi:[1,0]
	v_pk_mul_f32 v[60:61], v[60:61], v[98:99] op_sel_hi:[1,0]
	v_pk_mul_f32 v[58:59], v[58:59], v[98:99] op_sel_hi:[1,0]
	v_pk_mul_f32 v[56:57], v[56:57], v[98:99] op_sel_hi:[1,0]
	v_pk_mul_f32 v[54:55], v[54:55], v[98:99] op_sel_hi:[1,0]
	v_pk_mul_f32 v[52:53], v[52:53], v[98:99] op_sel_hi:[1,0]
	v_pk_mul_f32 v[50:51], v[50:51], v[98:99] op_sel_hi:[1,0]
	v_pk_mul_f32 v[48:49], v[48:49], v[98:99] op_sel_hi:[1,0]
	v_pk_mul_f32 v[46:47], v[46:47], v[98:99] op_sel_hi:[1,0]
	v_pk_mul_f32 v[44:45], v[44:45], v[98:99] op_sel_hi:[1,0]
	v_pk_mul_f32 v[42:43], v[42:43], v[98:99] op_sel_hi:[1,0]
	v_pk_mul_f32 v[40:41], v[40:41], v[98:99] op_sel_hi:[1,0]
	v_pk_mul_f32 v[38:39], v[38:39], v[98:99] op_sel_hi:[1,0]
	v_pk_mul_f32 v[36:37], v[36:37], v[98:99] op_sel_hi:[1,0]
	v_pk_mul_f32 v[34:35], v[34:35], v[98:99] op_sel_hi:[1,0]

.LBB0_638:
	v_mov_b32_e32 v102, v101
	s_nop 1
	v_permlane32_swap_b32_e32 v102, v101
	v_max3_f32 v101, v200, v101, v102
	v_mul_f32_e32 v213, 0xbfb8aa3b, v101
	v_fmamk_f32 v82, v82, 0x3fb8aa3b, v213
	v_fmamk_f32 v83, v83, 0x3fb8aa3b, v213
	v_exp_f32_e32 v82, v82
	v_fmamk_f32 v84, v84, 0x3fb8aa3b, v213
	v_fmamk_f32 v85, v85, 0x3fb8aa3b, v213
	v_exp_f32_e32 v83, v83
	v_exp_f32_e32 v84, v84
	v_exp_f32_e32 v85, v85
	v_add_f32_e32 v103, 0, v82
	v_add_f32_e32 v103, v83, v103
	v_add_f32_e32 v103, v84, v103
	v_cvt_pk_bf16_f32 v82, v82, v83
	v_cvt_pk_bf16_f32 v83, v84, v85
	v_fmamk_f32 v84, v86, 0x3fb8aa3b, v213
	v_add_f32_e32 v103, v85, v103
	v_fmamk_f32 v85, v87, 0x3fb8aa3b, v213
	v_exp_f32_e32 v84, v84
	v_fmamk_f32 v86, v88, 0x3fb8aa3b, v213
	v_fmamk_f32 v87, v89, 0x3fb8aa3b, v213
	v_exp_f32_e32 v85, v85
	v_exp_f32_e32 v86, v86
	v_exp_f32_e32 v87, v87
	v_add_f32_e32 v88, v84, v103
	v_add_f32_e32 v88, v85, v88
	v_add_f32_e32 v88, v86, v88
	v_cvt_pk_bf16_f32 v84, v84, v85
	v_cvt_pk_bf16_f32 v85, v86, v87
	v_add_u32_e32 v86, 0x1000, v195
	ds_write2_b64 v86, v[82:83], v[84:85] offset0:64 offset1:66
	v_fmamk_f32 v82, v90, 0x3fb8aa3b, v213
	v_fmamk_f32 v83, v91, 0x3fb8aa3b, v213
	v_exp_f32_e32 v82, v82
	v_fmamk_f32 v84, v92, 0x3fb8aa3b, v213
	v_fmamk_f32 v85, v93, 0x3fb8aa3b, v213
	v_exp_f32_e32 v83, v83
	v_exp_f32_e32 v84, v84
	v_exp_f32_e32 v85, v85
	v_add_f32_e32 v88, v87, v88
	v_add_f32_e32 v87, v82, v88
	v_add_f32_e32 v87, v83, v87
	v_add_f32_e32 v87, v84, v87
	v_cvt_pk_bf16_f32 v82, v82, v83
	v_cvt_pk_bf16_f32 v83, v84, v85
	v_fmamk_f32 v84, v94, 0x3fb8aa3b, v213
	v_add_f32_e32 v87, v85, v87
	v_fmamk_f32 v85, v95, 0x3fb8aa3b, v213
	v_exp_f32_e32 v84, v84
	v_fmamk_f32 v88, v96, 0x3fb8aa3b, v213
	v_exp_f32_e32 v85, v85
	v_fmamk_f32 v89, v97, 0x3fb8aa3b, v213
	v_exp_f32_e32 v88, v88
	v_fmamk_f32 v66, v66, 0x3fb8aa3b, v213
	v_exp_f32_e32 v89, v89
	v_fmamk_f32 v67, v67, 0x3fb8aa3b, v213
	v_add_f32_e32 v87, v84, v87
	v_exp_f32_e32 v66, v66
	v_fmamk_f32 v68, v68, 0x3fb8aa3b, v213
	v_fmamk_f32 v69, v69, 0x3fb8aa3b, v213
	v_add_f32_e32 v87, v85, v87
	v_exp_f32_e32 v67, v67
	v_add_f32_e32 v87, v88, v87
	v_exp_f32_e32 v68, v68
	v_exp_f32_e32 v69, v69
	v_add_f32_e32 v87, v89, v87
	v_cvt_pk_bf16_f32 v84, v84, v85
	v_cvt_pk_bf16_f32 v85, v88, v89
	ds_write2_b64 v86, v[82:83], v[84:85] offset0:68 offset1:70
	v_add_f32_e32 v82, v66, v87
	v_add_f32_e32 v82, v67, v82
	v_add_f32_e32 v82, v68, v82
	v_cvt_pk_bf16_f32 v66, v66, v67
	v_cvt_pk_bf16_f32 v67, v68, v69
	v_fmamk_f32 v68, v70, 0x3fb8aa3b, v213
	v_add_f32_e32 v82, v69, v82
	v_fmamk_f32 v69, v71, 0x3fb8aa3b, v213
	v_fmamk_f32 v70, v72, 0x3fb8aa3b, v213
	v_fmamk_f32 v71, v73, 0x3fb8aa3b, v213
	v_exp_f32_e32 v68, v68
	v_exp_f32_e32 v69, v69
	v_exp_f32_e32 v70, v70
	v_exp_f32_e32 v71, v71
	v_add_f32_e32 v72, v68, v82
	v_add_f32_e32 v72, v69, v72
	v_cvt_pk_bf16_f32 v68, v68, v69
	v_cvt_pk_bf16_f32 v69, v70, v71
	ds_write2_b64 v86, v[66:67], v[68:69] offset0:72 offset1:74
	v_fmamk_f32 v66, v74, 0x3fb8aa3b, v213
	v_fmamk_f32 v67, v75, 0x3fb8aa3b, v213
	v_exp_f32_e32 v66, v66
	v_fmamk_f32 v68, v76, 0x3fb8aa3b, v213
	v_exp_f32_e32 v67, v67
	v_fmamk_f32 v69, v77, 0x3fb8aa3b, v213
	v_add_f32_e32 v72, v70, v72
	v_exp_f32_e32 v68, v68
	v_add_f32_e32 v72, v71, v72
	v_exp_f32_e32 v69, v69
	v_add_f32_e32 v70, v66, v72
	v_add_f32_e32 v70, v67, v70
	v_add_f32_e32 v70, v68, v70
	v_add_f32_e32 v72, v69, v70
	v_cvt_pk_bf16_f32 v70, v66, v67
	v_fmamk_f32 v67, v79, 0x3fb8aa3b, v213
	v_fmamk_f32 v66, v78, 0x3fb8aa3b, v213
	v_cvt_pk_bf16_f32 v71, v68, v69
	v_exp_f32_e32 v68, v67
	v_fmamk_f32 v67, v80, 0x3fb8aa3b, v213
	v_exp_f32_e32 v66, v66
	v_exp_f32_e32 v69, v67
	v_fmamk_f32 v67, v81, 0x3fb8aa3b, v213
	v_exp_f32_e32 v73, v67
	v_add_f32_e32 v67, v66, v72
	v_add_f32_e32 v67, v68, v67
	v_sub_f32_e32 v102, v200, v101
	v_add_f32_e32 v67, v69, v67
	v_mul_f32_e32 v102, 0x3fb8aa3b, v102
	v_add_f32_e32 v67, v73, v67
	v_cvt_pk_bf16_f32 v72, v66, v68
	v_exp_f32_e32 v66, v102
	ds_bpermute_b32 v68, v171, v67
	v_cvt_pk_bf16_f32 v73, v69, v73
	ds_write2_b64 v86, v[70:71], v[72:73] offset0:76 offset1:78
	v_cmp_neq_f32_e32 vcc, 1.0, v66
	s_cbranch_vccz .LBB0_640
	v_pk_mul_f32 v[32:33], v[32:33], v[66:67] op_sel_hi:[1,0]
	v_pk_mul_f32 v[30:31], v[30:31], v[66:67] op_sel_hi:[1,0]
	v_pk_mul_f32 v[28:29], v[28:29], v[66:67] op_sel_hi:[1,0]
	v_pk_mul_f32 v[26:27], v[26:27], v[66:67] op_sel_hi:[1,0]
	v_pk_mul_f32 v[24:25], v[24:25], v[66:67] op_sel_hi:[1,0]
	v_pk_mul_f32 v[22:23], v[22:23], v[66:67] op_sel_hi:[1,0]
	v_pk_mul_f32 v[20:21], v[20:21], v[66:67] op_sel_hi:[1,0]
	v_pk_mul_f32 v[18:19], v[18:19], v[66:67] op_sel_hi:[1,0]
	v_pk_mul_f32 v[16:17], v[16:17], v[66:67] op_sel_hi:[1,0]
	v_pk_mul_f32 v[14:15], v[14:15], v[66:67] op_sel_hi:[1,0]
	v_pk_mul_f32 v[12:13], v[12:13], v[66:67] op_sel_hi:[1,0]
	v_pk_mul_f32 v[10:11], v[10:11], v[66:67] op_sel_hi:[1,0]
	v_pk_mul_f32 v[8:9], v[8:9], v[66:67] op_sel_hi:[1,0]
	v_pk_mul_f32 v[6:7], v[6:7], v[66:67] op_sel_hi:[1,0]
	v_pk_mul_f32 v[4:5], v[4:5], v[66:67] op_sel_hi:[1,0]
	v_pk_mul_f32 v[2:3], v[2:3], v[66:67] op_sel_hi:[1,0]
